# grid barrier spin loops: s_sleep 4 between flag polls (less polling traffic)
# speedup vs baseline: 1.0090x; 1.0090x over previous
.LBB0_1027:
	s_and_b32 s22, s4, 0xff
	s_mov_b64 s[20:21], -1
	s_cmp_lg_u32 s22, 0
	s_mov_b64 s[24:25], -1
	s_sleep 4
	s_cbranch_scc0 .LBB0_1030
	s_and_b64 vcc, exec, s[24:25]
	s_cbranch_vccz .LBB0_1026
